# per-XCD barrier counters placed 64 KiB apart (different memory channels) instead of 256 B apart; zeroed in-kernel at entry
# baseline (speedup 1.0000x reference)
; __device__ __forceinline__ int hw_lane() { int l = (int)__builtin_amdgcn_mbcnt_hi(~0u, __builtin_amdgcn_mbcnt_lo(~0u, 0u)); asm volatile("" : "+v"(l)); return l; }
; __device__ __forceinline__ gptr_t opq_ptr(const void* p) { gptr_t g = (gptr_t)p; asm volatile("" : "+s"(g)); return g; }
; __global__ void __launch_bounds__(NTHR, 2) hybrid_fwd(Args args) {
;     ...
;     const int wave = __builtin_amdgcn_readfirstlane((int)threadIdx.x >> 6);
;     grid.sync();
;     const int G = gridDim.x, blk = blockIdx.x;
;     unsigned bar_target = 0;
;     ...
;     unsigned xbar_target = 0;
;     int use_xcd = 0;
;     if (wave == 0 && hw_lane() == 0) __hip_atomic_store((unsigned*)opq_ptr(args.ws) + 2048 + blk, (unsigned)__builtin_amdgcn_s_getreg((3 << 11) | 20) & 0xFu, __ATOMIC_RELAXED, __HIP_MEMORY_SCOPE_AGENT);
_Z10hybrid_fwd4Args:
	s_load_dword s20, s[0:1], 0xb0
	v_and_b32_e32 v1, 0x3ff, v0
	s_nop 1
	v_readfirstlane_b32 s72, v1
	s_waitcnt lgkmcnt(0)
	s_cmp_lt_u32 s72, 64
	s_mov_b32 s33, s20
	s_cselect_b64 s[22:23], -1, 0
	s_cmp_gt_u32 s72, 63
	v_mbcnt_lo_u32_b32 v0, -1, 0
	s_cbranch_scc1 .LBB0_14
	v_mbcnt_hi_u32_b32 v1, -1, v0
	s_nop 0
	v_cmp_eq_u32_e32 vcc, 0, v1
	s_and_saveexec_b64 s[4:5], vcc
	s_cbranch_execz .LBB0_13
	s_load_dwordx2 s[6:7], s[0:1], 0xa8
	s_ashr_i32 s3, s2, 31
	s_lshl_b64 s[8:9], s[2:3], 2
	s_waitcnt lgkmcnt(0)
	s_cmp_gt_u32 s2, 7
	s_cbranch_scc1 .Lzc_skip
	s_lshl_b32 s10, s2, 16
	v_mov_b32_e32 v1, s10
	v_mov_b32_e32 v2, 0
	global_store_dword v1, v2, s[6:7] offset:256 sc1
	s_nop 1
.Lzc_skip:
	s_getreg_b32 s3, hwreg(HW_REG_XCC_ID, 0, 4)
	s_add_u32 s6, s6, s8
	s_addc_u32 s7, s7, s9
	s_and_b32 s3, s3, 15
	v_mov_b32_e32 v1, 0x2000
	v_mov_b32_e32 v2, s3
	global_store_dword v1, v2, s[6:7] sc1

; __device__ __forceinline__ void xcd_local_bar(unsigned* ctr, unsigned target, bool leader) {
;     asm volatile("s_waitcnt vmcnt(0) lgkmcnt(0)" ::: "memory");
;     __syncthreads();
;     if (leader) {
;         __hip_atomic_fetch_add(ctr, 1u, __ATOMIC_RELAXED, __HIP_MEMORY_SCOPE_AGENT);
;         while (__hip_atomic_load(ctr, __ATOMIC_RELAXED, __HIP_MEMORY_SCOPE_AGENT) < target) __builtin_amdgcn_s_sleep(1);
.Ldef_pub_done:
.Ldef_skip:
	s_cmp_lg_u32 s76, 0
	s_cselect_b64 s[12:13], -1, 0
	s_lshr_b32 s8, s21, 29
	s_add_i32 s8, s20, s8
	s_ashr_i32 s54, s8, 3
	s_lshl_b32 s8, s2, 6
	s_and_b32 s8, s8, 0x1c0
	s_lshl_b32 s8, s8, 8
	s_cmp_eq_u32 s76, 0
	v_writelane_b32 v248, s8, 4
	s_cbranch_scc1 .LBB0_360
	s_mov_b64 s[10:11], s[18:19]
	s_and_b64 vcc, exec, s[4:5]
	s_mov_b64 s[14:15], 0
	s_cbranch_vccnz .LBB0_352
	v_mov_b32_e32 v0, v212
	s_nop 0
	v_cmp_eq_u32_e32 vcc, 0, v0
	s_and_b64 s[14:15], vcc, exec
